# out-proj main loop rewritten: one K block per barrier through the 4-slot ring with three blocks in flight, rotated, scalar-side DMA addressing
# speedup vs baseline: 1.2227x; 1.0074x over previous
; DI int otid() { int t = threadIdx.x; asm volatile("" : "+v"(t)); return t; }
; #define G_ISSUE(ks_, buf_) do { \
;     const bf16_t* wq_ = wp + (ks_) * wks; const bf16_t* xq_ = xp + (ks_) * xks; char* lb_ = ld + (buf_) * STAGE; \
;     dma16(wq_, lb_); dma16(wq_ + 2048, lb_ + 4096); \
;     _Pragma("unroll") for (int i_ = 0; i_ < TJ; ++i_) dma16(xq_ + i_ * 2048, lb_ + 8192 + i_ * 4096); } while (0)
; template <bool VMODE, int TJ>
; DI void gemm_mainloop(const bf16_t* __restrict__ W, const bf16_t* __restrict__ X, int NW, char* smem, f32x16 (&acc)[2][TJ]) {
;     constexpr int XROWS = 64 * TJ, STAGE = (128 + XROWS) * 64, NPW = 2 + TJ;
;     const int tid = otid(), lane = tid & 63, wave = tid >> 6, r = lane & 31, h = lane >> 5, wf = wave & 1, wt = wave >> 1;
;     const int goff = (16 * wave + (lane >> 2)) * 32 + (((lane & 3) ^ (lane >> 4)) << 3);
;     const bf16_t* wp = W + goff;
;     const bf16_t* xp = X + goff;
;     const size_t wks = (size_t)NW * 32, xks = (size_t)NTOK * 32;
;     char* ld = smem + tid * 16;
;     ...
;     const int xr = (r >> 2) & 3;
;     const int fo0 = r * 64 + (((0 + h) ^ xr) << 4), fo1 = r * 64 + (((2 + h) ^ xr) << 4);
;     __syncthreads();
;     ...
;     if (TJ <= 2) {
;         constexpr int NSL = (TJ == 1) ? 6 : 4;
;         G_ISSUE(0, 0);
;         G_ISSUE(1, 1);
;         if (TJ == 1) { G_ISSUE(2, 2); G_ISSUE(3, 3); }
;         int sl = 0;
;         for (int kp = 0; kp < 16; ++kp) {
;             if (TJ == 1 && kp + 1 < 16) asm volatile("s_waitcnt vmcnt(6)" ::: "memory");
;             else asm volatile("s_waitcnt vmcnt(0)" ::: "memory");
;             __builtin_amdgcn_s_barrier();
.LBB0_20:
	s_ashr_i32 s4, s50, 31
	s_lshr_b32 s4, s4, 29
	s_add_i32 s4, s50, s4
	s_ashr_i32 s4, s4, 3
	s_mul_hi_i32 s5, s4, 0x38e38e39
	s_lshr_b32 s6, s5, 31
	s_ashr_i32 s5, s5, 2
	s_add_i32 s5, s5, s6
	s_mul_i32 s5, s5, 18
	s_sub_i32 s5, s4, s5
	s_cmp_lt_i32 s5, 16
	s_cselect_b64 s[6:7], -1, 0
	s_or_b64 s[8:9], s[48:49], s[6:7]
	s_andn2_b64 vcc, exec, s[8:9]
	s_cbranch_vccnz .LBB0_19
	v_mov_b32_e32 v116, v200
	s_load_dwordx2 s[34:35], s[0:1], 0xb8
	s_load_dwordx2 s[28:29], s[0:1], 0xd8
	s_lshl_b32 s4, s4, 3
	s_sub_i32 s8, s50, s4
	s_mul_hi_i32 s4, s50, 0x38e38e39
	s_lshr_b32 s9, s4, 31
	s_ashr_i32 s4, s4, 5
	s_add_i32 s4, s4, s9
	s_lshl_b32 s40, s5, 7
	s_lshl_b32 s8, s8, 7
	s_waitcnt lgkmcnt(0)
	s_add_u32 s5, s28, s44
	s_addc_u32 s41, s29, s45
	s_ashr_i32 s9, s8, 31
	s_lshl_b64 s[28:29], s[8:9], 6
	s_add_u32 s28, s5, s28
	v_mov_b32_e32 v8, v200
	s_addc_u32 s29, s41, s29
	s_ashr_i32 s5, s4, 31
	s_mul_i32 s42, s4, 0x900
	s_ashr_i32 s43, s40, 31
	s_mul_hi_i32 s41, s4, 0x900
	v_bfe_u32 v1, v8, 4, 2
	s_add_u32 s42, s42, s40
	v_bitop3_b32 v1, v1, v8, 3 bitop3:0x78
	s_addc_u32 s43, s41, s43
	v_lshlrev_b32_e32 v0, 3, v8
	v_lshlrev_b32_e32 v1, 3, v1
	s_movk_i32 s41, 0xffe0
	v_and_or_b32 v0, v0, s41, v1
	v_ashrrev_i32_e32 v1, 31, v0
	v_lshl_add_u32 v66, v8, 4, 32
	v_lshlrev_b64 v[64:65], 1, v[0:1]
	v_readfirstlane_b32 s41, v66
	v_add_u32_e32 v6, 0x1000, v66
	v_lshl_add_u64 v[0:1], s[28:29], 0, v[64:65]
	s_mov_b32 m0, s41
	v_readfirstlane_b32 s41, v6
	s_lshl_b64 s[42:43], s[42:43], 6
	s_barrier
	global_load_lds_dwordx4 v[0:1], off
	v_lshl_add_u64 v[4:5], v[0:1], 0, s[26:27]
	s_mov_b32 m0, s41
	s_add_u32 s34, s34, s42
	global_load_lds_dwordx4 v[4:5], off
	v_add_u32_e32 v4, 0x2000, v66
	s_addc_u32 s35, s35, s43
	v_readfirstlane_b32 s41, v4
	v_add_u32_e32 v6, 0x3000, v66
	v_lshl_add_u64 v[2:3], s[34:35], 0, v[64:65]
	s_mov_b32 m0, s41
	v_readfirstlane_b32 s41, v6
	v_add_u32_e32 v9, 0x4000, v66
	global_load_lds_dwordx4 v[2:3], off
	v_lshl_add_u64 v[4:5], v[2:3], 0, s[26:27]
	s_mov_b32 m0, s41
	s_mov_b64 s[42:43], 0x10000
	v_readfirstlane_b32 s41, v9
	global_load_lds_dwordx4 v[4:5], off
	v_lshl_add_u64 v[4:5], v[0:1], 0, s[42:43]
	s_mov_b32 m0, s41
	s_mov_b64 s[42:43], 0x120000
	global_load_lds_dwordx4 v[4:5], off
	v_add_u32_e32 v4, 0x5000, v66
	v_lshl_add_u64 v[6:7], v[2:3], 0, s[42:43]
	s_mov_b64 s[42:43], 0x11000
	v_readfirstlane_b32 s41, v4
	v_lshl_add_u64 v[0:1], v[0:1], 0, s[42:43]
	s_mov_b32 m0, s41
	s_mov_b64 s[42:43], 0x121000
	global_load_lds_dwordx4 v[0:1], off
	v_add_u32_e32 v0, 0x6000, v66
	s_nop 0
	v_readfirstlane_b32 s41, v0
	v_lshl_add_u64 v[0:1], v[2:3], 0, s[42:43]
	v_add_u32_e32 v2, 0x7000, v66
	s_mov_b32 m0, s41
	v_readfirstlane_b32 s41, v2
	global_load_lds_dwordx4 v[6:7], off
	s_mov_b32 m0, s41
	v_bfe_u32 v2, v8, 2, 2
	global_load_lds_dwordx4 v[0:1], off
	v_bfe_u32 v0, v8, 5, 1
	v_lshrrev_b32_e32 v1, 2, v8
	v_lshlrev_b32_e32 v3, 6, v8
	v_bitop3_b32 v1, v0, v1, 3 bitop3:0x78
	v_bitop3_b32 v0, v0, v2, 2 bitop3:0x36
	v_and_b32_e32 v2, 0x7c0, v3
	v_lshl_or_b32 v67, v0, 4, v2
	v_lshlrev_b32_e32 v0, 5, v8
	v_and_b32_e32 v69, 0xfffff000, v0
	v_mov_b32_e32 v0, 0
	v_lshl_or_b32 v68, v1, 4, v2
	v_and_b32_e32 v70, 0x1000, v3
	s_mov_b32 s42, 0
	s_mov_b32 s41, 15
	v_mov_b32_e32 v1, v0
	v_mov_b32_e32 v2, v0
	v_mov_b32_e32 v3, v0
	v_mov_b32_e32 v4, v0
	v_mov_b32_e32 v5, v0
	v_mov_b32_e32 v6, v0
	v_mov_b32_e32 v7, v0
	v_mov_b32_e32 v8, v0
	v_mov_b32_e32 v9, v0
	v_mov_b32_e32 v10, v0
	v_mov_b32_e32 v11, v0
	v_mov_b32_e32 v12, v0
	v_mov_b32_e32 v13, v0
	v_mov_b32_e32 v14, v0
	v_mov_b32_e32 v15, v0
	v_mov_b32_e32 v16, v0
	v_mov_b32_e32 v17, v0
	v_mov_b32_e32 v18, v0
	v_mov_b32_e32 v19, v0
	v_mov_b32_e32 v20, v0
	v_mov_b32_e32 v21, v0
	v_mov_b32_e32 v22, v0
	v_mov_b32_e32 v23, v0
	v_mov_b32_e32 v24, v0
	v_mov_b32_e32 v25, v0
	v_mov_b32_e32 v26, v0
	v_mov_b32_e32 v27, v0
	v_mov_b32_e32 v28, v0
	v_mov_b32_e32 v29, v0
	v_mov_b32_e32 v30, v0
	v_mov_b32_e32 v31, v0
	v_mov_b32_e32 v32, v0
	v_mov_b32_e32 v33, v0
	v_mov_b32_e32 v34, v0
	v_mov_b32_e32 v35, v0
	v_mov_b32_e32 v36, v0
	v_mov_b32_e32 v37, v0
	v_mov_b32_e32 v38, v0
	v_mov_b32_e32 v39, v0
	v_mov_b32_e32 v40, v0
	v_mov_b32_e32 v41, v0
	v_mov_b32_e32 v42, v0
	v_mov_b32_e32 v43, v0
	v_mov_b32_e32 v44, v0
	v_mov_b32_e32 v45, v0
	v_mov_b32_e32 v46, v0
	v_mov_b32_e32 v47, v0
	v_mov_b32_e32 v48, v0
	v_mov_b32_e32 v49, v0
	v_mov_b32_e32 v50, v0
	v_mov_b32_e32 v51, v0
	v_mov_b32_e32 v52, v0
	v_mov_b32_e32 v53, v0
	v_mov_b32_e32 v54, v0
	v_mov_b32_e32 v55, v0
	v_mov_b32_e32 v56, v0
	v_mov_b32_e32 v57, v0
	v_mov_b32_e32 v58, v0
	v_mov_b32_e32 v59, v0
	v_mov_b32_e32 v60, v0
	v_mov_b32_e32 v61, v0
	v_mov_b32_e32 v62, v0
	v_mov_b32_e32 v63, v0
	v_readfirstlane_b32 s100, v66
	v_add_u32_e32 v101, 0x1000, v64
	v_add_u32_e32 v106, v70, v68
	v_add_u32_e32 v107, v69, v68
	v_add_u32_e32 v108, v70, v67
	v_add_u32_e32 v109, v69, v67
	s_add_u32 s28, s28, 0x20000
	s_addc_u32 s29, s29, 0
	s_add_u32 s34, s34, 0x240000
	s_addc_u32 s35, s35, 0
	s_add_i32 s101, s100, 0x8000
	s_mov_b32 m0, s101
	s_nop 0
	global_load_lds_dwordx4 v64, s[28:29]
	s_add_u32 m0, s101, 0x1000
	s_nop 0
	global_load_lds_dwordx4 v101, s[28:29]
	s_add_u32 m0, s101, 0x2000
	s_nop 0
	global_load_lds_dwordx4 v64, s[34:35]
	s_add_u32 m0, s101, 0x3000
	s_nop 0
	global_load_lds_dwordx4 v101, s[34:35]
	s_add_u32 s28, s28, 0x10000
	s_addc_u32 s29, s29, 0
	s_add_u32 s34, s34, 0x120000
	s_addc_u32 s35, s35, 0
	s_mov_b32 s42, 0
	s_mov_b32 s41, 28
	s_lshl_b32 s43, s42, 14
	s_add_i32 s43, s43, 32
	v_add_u32_e32 v110, s43, v106
	v_add_u32_e32 v111, s43, v107
	v_add_u32_e32 v112, s43, v108
	v_add_u32_e32 v113, s43, v109
	s_waitcnt vmcnt(8)
	s_waitcnt lgkmcnt(0)
	s_barrier
	ds_read_b128 v[72:75], v110
	ds_read_b128 v[76:79], v110 offset:2048
	ds_read_b128 v[80:83], v111 offset:8192
	ds_read_b128 v[84:87], v111 offset:10240
	s_add_i32 s43, s42, 3
	s_and_b32 s43, s43, 3
	s_lshl_b32 s43, s43, 14
	s_add_i32 s101, s43, s100
	s_mov_b32 m0, s101
	s_add_i32 s42, s42, 1
	s_and_b32 s42, s42, 3
	s_nop 0
	global_load_lds_dwordx4 v64, s[28:29]
	s_add_u32 m0, s101, 0x1000
	s_nop 0
	global_load_lds_dwordx4 v101, s[28:29]
	s_add_u32 m0, s101, 0x2000
	s_nop 0
	global_load_lds_dwordx4 v64, s[34:35]
	s_add_u32 m0, s101, 0x3000
	s_nop 0
	global_load_lds_dwordx4 v101, s[34:35]
	s_add_u32 s28, s28, 0x10000
	s_addc_u32 s29, s29, 0
	s_add_u32 s34, s34, 0x120000
	s_addc_u32 s35, s35, 0
	s_waitcnt lgkmcnt(0)
	v_mfma_f32_32x32x16_bf16 v[48:63], v[72:75], v[80:83], v[48:63]
	ds_read_b128 v[120:123], v112
	v_mfma_f32_32x32x16_bf16 v[32:47], v[72:75], v[84:87], v[32:47]
	ds_read_b128 v[128:131], v113 offset:8192
	v_mfma_f32_32x32x16_bf16 v[16:31], v[76:79], v[80:83], v[16:31]
	ds_read_b128 v[124:127], v112 offset:2048
	v_mfma_f32_32x32x16_bf16 v[0:15], v[76:79], v[84:87], v[0:15]
	ds_read_b128 v[132:135], v113 offset:10240
; #define MFMA(a, b, c) __builtin_amdgcn_mfma_f32_32x32x16_bf16((a), (b), (c), 0, 0, 0)
; template <bool VMODE, int TJ>
; DI void gemm_mainloop(const bf16_t* __restrict__ W, const bf16_t* __restrict__ X, int NW, char* smem, f32x16 (&acc)[2][TJ]) {
;     ...
;     if (TJ <= 2) {
;         constexpr int NSL = (TJ == 1) ? 6 : 4;
;         G_ISSUE(0, 0);
;         G_ISSUE(1, 1);
;         if (TJ == 1) { G_ISSUE(2, 2); G_ISSUE(3, 3); }
;         int sl = 0;
;         for (int kp = 0; kp < 16; ++kp) {
;             if (TJ == 1 && kp + 1 < 16) asm volatile("s_waitcnt vmcnt(6)" ::: "memory");
;             else asm volatile("s_waitcnt vmcnt(0)" ::: "memory");
;             __builtin_amdgcn_s_barrier();
;             const int sn2 = (TJ == 1) ? ((sl + 4 >= NSL) ? sl + 4 - NSL : sl + 4) : 2 - sl;
;             {
;                 const char* sw = smem + sl * STAGE + wf * 64 * 64;
;                 const char* sx = smem + sl * STAGE + 8192 + wt * (32 * TJ) * 64;
;                 bf16x8 fw[2], fx[TJ];
; #pragma unroll
;                 for (int i = 0; i < 2; ++i) fw[i] = *(const bf16x8*)(sw + i * 32 * 64 + fo0);
; #pragma unroll
;                 for (int j = 0; j < TJ; ++j) fx[j] = *(const bf16x8*)(sx + j * 32 * 64 + fo0);
;                 __builtin_amdgcn_sched_barrier(0);
;                 if (TJ == 1) { if (kp + 2 < 16) { G_ISSUE(2 * kp + 4, sn2); G_ISSUE(2 * kp + 5, sn2 + 1); } }
;                 else if (kp + 1 < 16) { G_ISSUE(2 * kp + 2, sn2); G_ISSUE(2 * kp + 3, sn2 + 1); }
;                 __builtin_amdgcn_sched_barrier(0);
; #pragma unroll
;                 for (int i = 0; i < 2; ++i)
; #pragma unroll
;                     for (int j = 0; j < TJ; ++j) acc[i][j] = VMODE ? MFMA(fx[j], fw[i], acc[i][j]) : MFMA(fw[i], fx[j], acc[i][j]);
; #pragma unroll
;                 for (int i = 0; i < 2; ++i) fw[i] = *(const bf16x8*)(sw + i * 32 * 64 + fo1);
; #pragma unroll
;                 for (int j = 0; j < TJ; ++j) fx[j] = *(const bf16x8*)(sx + j * 32 * 64 + fo1);
; #pragma unroll
;                 for (int i = 0; i < 2; ++i)
; #pragma unroll
;                     for (int j = 0; j < TJ; ++j) acc[i][j] = VMODE ? MFMA(fx[j], fw[i], acc[i][j]) : MFMA(fw[i], fx[j], acc[i][j]);
;             }
;             G_COMPUTE(sl + 1);
;             sl = (sl + 2 >= NSL) ? 0 : sl + 2;
;         }
.Lop_loop:
	s_lshl_b32 s43, s42, 14
	s_add_i32 s43, s43, 32
	v_add_u32_e32 v110, s43, v106
	v_add_u32_e32 v111, s43, v107
	v_add_u32_e32 v112, s43, v108
	v_add_u32_e32 v113, s43, v109
	s_waitcnt vmcnt(8)
	s_waitcnt lgkmcnt(0)
	s_barrier
	ds_read_b128 v[72:75], v110
	ds_read_b128 v[76:79], v110 offset:2048
	ds_read_b128 v[80:83], v111 offset:8192
	ds_read_b128 v[84:87], v111 offset:10240
	s_add_i32 s43, s42, 3
	s_and_b32 s43, s43, 3
	s_lshl_b32 s43, s43, 14
	s_add_i32 s101, s43, s100
	s_mov_b32 m0, s101
	s_add_i32 s42, s42, 1
	s_and_b32 s42, s42, 3
	v_mfma_f32_32x32x16_bf16 v[48:63], v[120:123], v[128:131], v[48:63]
	global_load_lds_dwordx4 v64, s[28:29]
	s_add_u32 m0, s101, 0x1000
	v_mfma_f32_32x32x16_bf16 v[32:47], v[120:123], v[132:135], v[32:47]
	global_load_lds_dwordx4 v101, s[28:29]
	s_add_u32 m0, s101, 0x2000
	v_mfma_f32_32x32x16_bf16 v[16:31], v[124:127], v[128:131], v[16:31]
	global_load_lds_dwordx4 v64, s[34:35]
	s_add_u32 m0, s101, 0x3000
	v_mfma_f32_32x32x16_bf16 v[0:15], v[124:127], v[132:135], v[0:15]
	global_load_lds_dwordx4 v101, s[34:35]
	s_add_u32 s28, s28, 0x10000
	s_addc_u32 s29, s29, 0
	s_add_u32 s34, s34, 0x120000
	s_addc_u32 s35, s35, 0
	s_waitcnt lgkmcnt(0)
	v_mfma_f32_32x32x16_bf16 v[48:63], v[72:75], v[80:83], v[48:63]
	ds_read_b128 v[120:123], v112
	v_mfma_f32_32x32x16_bf16 v[32:47], v[72:75], v[84:87], v[32:47]
	ds_read_b128 v[128:131], v113 offset:8192
	v_mfma_f32_32x32x16_bf16 v[16:31], v[76:79], v[80:83], v[16:31]
	ds_read_b128 v[124:127], v112 offset:2048
	v_mfma_f32_32x32x16_bf16 v[0:15], v[76:79], v[84:87], v[0:15]
	ds_read_b128 v[132:135], v113 offset:10240
	s_add_i32 s41, s41, -1
	s_cmp_lg_u32 s41, 0
	s_cbranch_scc1 .Lop_loop
	s_lshl_b32 s43, s42, 14
	s_add_i32 s43, s43, 32
	v_add_u32_e32 v110, s43, v106
	v_add_u32_e32 v111, s43, v107
	v_add_u32_e32 v112, s43, v108
	v_add_u32_e32 v113, s43, v109
	s_waitcnt vmcnt(8)
	s_waitcnt lgkmcnt(0)
	s_barrier
	ds_read_b128 v[72:75], v110
	ds_read_b128 v[76:79], v110 offset:2048
	ds_read_b128 v[80:83], v111 offset:8192
	ds_read_b128 v[84:87], v111 offset:10240
	s_add_i32 s42, s42, 1
	s_and_b32 s42, s42, 3
	v_mfma_f32_32x32x16_bf16 v[48:63], v[120:123], v[128:131], v[48:63]
	v_mfma_f32_32x32x16_bf16 v[32:47], v[120:123], v[132:135], v[32:47]
	v_mfma_f32_32x32x16_bf16 v[16:31], v[124:127], v[128:131], v[16:31]
	v_mfma_f32_32x32x16_bf16 v[0:15], v[124:127], v[132:135], v[0:15]
	s_waitcnt lgkmcnt(0)
	v_mfma_f32_32x32x16_bf16 v[48:63], v[72:75], v[80:83], v[48:63]
	ds_read_b128 v[120:123], v112
	v_mfma_f32_32x32x16_bf16 v[32:47], v[72:75], v[84:87], v[32:47]
	ds_read_b128 v[128:131], v113 offset:8192
	v_mfma_f32_32x32x16_bf16 v[16:31], v[76:79], v[80:83], v[16:31]
	ds_read_b128 v[124:127], v112 offset:2048
	v_mfma_f32_32x32x16_bf16 v[0:15], v[76:79], v[84:87], v[0:15]
	ds_read_b128 v[132:135], v113 offset:10240
	s_lshl_b32 s43, s42, 14
	s_add_i32 s43, s43, 32
	v_add_u32_e32 v110, s43, v106
	v_add_u32_e32 v111, s43, v107
	v_add_u32_e32 v112, s43, v108
	v_add_u32_e32 v113, s43, v109
	s_waitcnt vmcnt(4)
	s_waitcnt lgkmcnt(0)
	s_barrier
	ds_read_b128 v[72:75], v110
	ds_read_b128 v[76:79], v110 offset:2048
	ds_read_b128 v[80:83], v111 offset:8192
	ds_read_b128 v[84:87], v111 offset:10240
	s_add_i32 s42, s42, 1
	s_and_b32 s42, s42, 3
	v_mfma_f32_32x32x16_bf16 v[48:63], v[120:123], v[128:131], v[48:63]
	v_mfma_f32_32x32x16_bf16 v[32:47], v[120:123], v[132:135], v[32:47]
	v_mfma_f32_32x32x16_bf16 v[16:31], v[124:127], v[128:131], v[16:31]
	v_mfma_f32_32x32x16_bf16 v[0:15], v[124:127], v[132:135], v[0:15]
	s_waitcnt lgkmcnt(0)
	v_mfma_f32_32x32x16_bf16 v[48:63], v[72:75], v[80:83], v[48:63]
	ds_read_b128 v[120:123], v112
	v_mfma_f32_32x32x16_bf16 v[32:47], v[72:75], v[84:87], v[32:47]
	ds_read_b128 v[128:131], v113 offset:8192
	v_mfma_f32_32x32x16_bf16 v[16:31], v[76:79], v[80:83], v[16:31]
	ds_read_b128 v[124:127], v112 offset:2048
	v_mfma_f32_32x32x16_bf16 v[0:15], v[76:79], v[84:87], v[0:15]
	ds_read_b128 v[132:135], v113 offset:10240
	s_lshl_b32 s43, s42, 14
	s_add_i32 s43, s43, 32
	v_add_u32_e32 v110, s43, v106
	v_add_u32_e32 v111, s43, v107
	v_add_u32_e32 v112, s43, v108
	v_add_u32_e32 v113, s43, v109
	s_waitcnt vmcnt(0)
	s_waitcnt lgkmcnt(0)
	s_barrier
	ds_read_b128 v[72:75], v110
	ds_read_b128 v[76:79], v110 offset:2048
	ds_read_b128 v[80:83], v111 offset:8192
	ds_read_b128 v[84:87], v111 offset:10240
	s_add_i32 s42, s42, 1
	s_and_b32 s42, s42, 3
	v_mfma_f32_32x32x16_bf16 v[48:63], v[120:123], v[128:131], v[48:63]
	v_mfma_f32_32x32x16_bf16 v[32:47], v[120:123], v[132:135], v[32:47]
	v_mfma_f32_32x32x16_bf16 v[16:31], v[124:127], v[128:131], v[16:31]
	v_mfma_f32_32x32x16_bf16 v[0:15], v[124:127], v[132:135], v[0:15]
	s_waitcnt lgkmcnt(0)
	v_mfma_f32_32x32x16_bf16 v[48:63], v[72:75], v[80:83], v[48:63]
	ds_read_b128 v[120:123], v112
	v_mfma_f32_32x32x16_bf16 v[32:47], v[72:75], v[84:87], v[32:47]
	ds_read_b128 v[128:131], v113 offset:8192
	v_mfma_f32_32x32x16_bf16 v[16:31], v[76:79], v[80:83], v[16:31]
	ds_read_b128 v[124:127], v112 offset:2048
	v_mfma_f32_32x32x16_bf16 v[0:15], v[76:79], v[84:87], v[0:15]
	ds_read_b128 v[132:135], v113 offset:10240
	s_waitcnt lgkmcnt(0)
	v_mfma_f32_32x32x16_bf16 v[48:63], v[120:123], v[128:131], v[48:63]
	v_mfma_f32_32x32x16_bf16 v[32:47], v[120:123], v[132:135], v[32:47]
	s_waitcnt vmcnt(0) lgkmcnt(0)
	s_barrier
	s_mov_b64 s[34:35], -1
	s_and_b64 vcc, exec, s[46:47]
	s_load_dwordx2 s[28:29], s[0:1], 0xe0
	v_mfma_f32_32x32x16_bf16 v[16:31], v[124:127], v[128:131], v[16:31]
	v_mfma_f32_32x32x16_bf16 v[0:15], v[124:127], v[132:135], v[0:15]
	v_ashrrev_i32_e32 v64, 1, v116
	v_and_b32_e32 v64, 0xffffffc0, v64
	v_add_u32_e32 v66, s40, v64
	v_cmp_gt_i32_e64 s[40:41], s61, v66
	v_cmp_lt_i32_e64 s[42:43], s21, v66
	s_cbranch_vccz .LBB0_29
	s_and_saveexec_b64 s[34:35], s[42:43]
	s_xor_b64 s[34:35], exec, s[34:35]
	v_add_u32_e32 v192, 0xfffff800, v66
	v_mov_b64_e32 v[68:69], v[192:193]
	s_or_saveexec_b64 s[34:35], s[34:35]
	v_readlane_b32 s52, v254, 7
	v_readlane_b32 s53, v254, 8
	v_mov_b64_e32 v[64:65], 20
	s_nop 0
	v_mov_b64_e32 v[70:71], s[52:53]
	s_xor_b64 exec, exec, s[34:35]
	s_cbranch_execz .LBB0_28
	v_readlane_b32 s52, v254, 9
	v_ashrrev_i32_e32 v67, 31, v66
	v_readlane_b32 s53, v254, 10
	v_mov_b64_e32 v[64:65], 23
	v_mov_b64_e32 v[68:69], v[66:67]
	v_mov_b64_e32 v[70:71], s[52:53]
